# attention loop: per-lane threshold check replaces per-tile cross-lane max + subtract, V-address constants hoisted out of the tile loop
# speedup vs baseline: 1.0195x; 1.0027x over previous
; DI void dattn_unit2(const bf16_t* __restrict__ Qg, const bf16_t* __restrict__ Kg, const bf16_t* __restrict__ Vg, bf16_t* __restrict__ Og,
;                     int ntiles, int wave_tiles, float lam, const float* __restrict__ gsub, lds_t* shm) {
;     ...
;   f32x16 O[2][NC];
; #pragma unroll
;   for (int m = 0; m < 2; ++m)
; #pragma unroll
;     for (int c = 0; c < NC; ++c)
; #pragma unroll
;       for (int i = 0; i < 16; ++i) O[m][c][i] = 0.f;
;   float mrun[2] = {-INFINITY, -INFINITY}, lrun[2] = {0.f, 0.f};
;   const unsigned q4 = (lane & 15) >> 2, pp = lane & 3, blk = (lane >> 4) & 1;
;   const unsigned xk = (l31 >> 2) & 3, kbase = 2048u * (l31 >> 3) + 64u * (l31 & 7);
;   const unsigned ka0 = kbase + 16u * ((unsigned)h ^ xk), ka2 = kbase + 16u * ((2u + h) ^ xk);
;   const unsigned vrow = 64u * (4u * h + q4), cl = 2u * blk + (pp >> 1);
;   const unsigned va0 = VRING + vrow + 16u * (cl ^ (unsigned)h) + 8u * (pp & 1), va1 = VRING + vrow + 16u * (cl ^ ((unsigned)h ^ 2u)) + 8u * (pp & 1);
;   WAIT_V(6); BAR;
;   if (grp == 1) { WAIT_V(4); BAR; }
;   int slot = 0;
;   for (int kt = 0; kt < ntiles; ++kt) {
;     const int slot2 = slot >= 1 ? slot - 1 : 2;
;     issueK(kt + 2, slot2);
;     const float msk = (kt < wave_tiles) ? 0.f : -INFINITY;
;     const unsigned so = slot * 16384;
;     lds_t* K0 = shm + (so + ka0); lds_t* K2 = shm + (so + ka2);
;     bf16x8 P[2][2][2]; float alpha[2]; bool resc[2];
; #pragma unroll
;     for (int m = 0; m < 2; ++m) {
;       f32x16 s[2];
; #pragma unroll
;       for (int kb = 0; kb < 2; ++kb)
; #pragma unroll
;         for (int i = 0; i < 16; ++i) s[kb][i] = 0.f;
; #pragma unroll
;       for (int ss = 0; ss < 4; ++ss) {
;         const bf16x8 qv = *LDSP(const bf16x8, Qst + ((ss & 1) ? ka2 : ka0) + 512 * (ss >> 1) + 1024 * m);
; #pragma unroll
;         for (int kb = 0; kb < 2; ++kb) {
;           const bf16x8 kf = *LDSP(const bf16x8, ((ss & 1) ? K2 : K0) + kb * 8192 + 512 * (ss >> 1) + 1024 * m);
;           s[kb] = MFMA32(kf, qv, s[kb]);
;         }
;       }
;       float mx = s[0][0];
; #pragma unroll
;       for (int i = 1; i < 16; ++i) mx = fmaxf(mx, s[0][i]);
; #pragma unroll
;       for (int i = 0; i < 16; ++i) mx = fmaxf(mx, s[1][i]);
;       { const auto sw = __builtin_amdgcn_permlane32_swap(__float_as_uint(mx), __float_as_uint(mx), false, false); mx = fmaxf(__uint_as_float(sw[0]), __uint_as_float(sw[1])) + msk; }
.LBB0_417:
	v_lshlrev_b32_e32 v7, 6, v0
	v_lshrrev_b32_e32 v4, 5, v0
	v_and_b32_e32 v3, 3, v3
	v_lshlrev_b32_e32 v6, 8, v0
	v_and_b32_e32 v7, 0x1c0, v7
	v_bfe_u32 v5, v0, 5, 1
	v_and_or_b32 v6, v6, s22, v7
	v_bitop3_b32 v4, v4, v3, 1 bitop3:0x6c
	v_lshl_or_b32 v218, v4, 4, v6
	v_or_b32_e32 v4, 2, v5
	v_bitop3_b32 v3, v5, v3, 2 bitop3:0x36
	v_and_b32_e32 v221, 0xc0, v1
	v_and_b32_e32 v1, 2, v2
	v_bfe_u32 v2, v0, 1, 1
	v_lshlrev_b32_e32 v0, 3, v0
	v_lshl_or_b32 v219, v3, 4, v6
	v_bitop3_b32 v3, v1, v5, v2 bitop3:0x36
	v_and_b32_e32 v223, 8, v0
	v_bitop3_b32 v0, v1, v4, v2 bitop3:0x36
	v_mov_b32_e32 v96, v193
	v_mov_b32_e32 v97, v193
	v_mov_b32_e32 v110, v193
	v_mov_b32_e32 v111, v193
	s_lshl_b32 s58, s54, 2
	v_lshlrev_b32_e32 v220, 8, v5
	v_lshlrev_b32_e32 v222, 4, v3
	v_lshlrev_b32_e32 v224, 4, v0
	v_mov_b32_e32 v98, v193
	v_mov_b32_e32 v99, v193
	v_mov_b32_e32 v100, v193
	v_mov_b32_e32 v101, v193
	v_mov_b32_e32 v102, v193
	v_mov_b32_e32 v103, v193
	v_mov_b32_e32 v104, v193
	v_mov_b32_e32 v105, v193
	v_mov_b32_e32 v106, v193
	v_mov_b32_e32 v107, v193
	v_mov_b32_e32 v108, v193
	v_mov_b32_e32 v109, v193
	v_mov_b32_e32 v198, 0xff800000
	v_mov_b32_e32 v200, 0
	v_mov_b64_e32 v[64:65], v[96:97]
	v_mov_b64_e32 v[32:33], v[96:97]
	v_mov_b64_e32 v[0:1], v[96:97]
	v_mov_b64_e32 v[126:127], v[110:111]
	v_mov_b64_e32 v[80:81], v[96:97]
	v_mov_b64_e32 v[48:49], v[96:97]
	v_mov_b64_e32 v[16:17], v[96:97]
	s_xor_b64 s[40:41], s[4:5], -1
	s_lshl_b64 s[42:43], s[6:7], 10
	v_mov_b32_e32 v197, v193
	s_add_i32 s54, s58, s19
	s_or_b32 s55, s58, 3
	s_add_i32 s58, s58, 4
	s_mov_b32 s59, 0
	v_add_u32_e32 v225, s52, v218
	v_mov_b64_e32 v[66:67], v[98:99]
	v_mov_b64_e32 v[68:69], v[100:101]
	v_mov_b64_e32 v[70:71], v[102:103]
	v_mov_b64_e32 v[72:73], v[104:105]
	v_mov_b64_e32 v[74:75], v[106:107]
	v_mov_b64_e32 v[76:77], v[108:109]
	v_mov_b64_e32 v[78:79], v[110:111]
	v_mov_b64_e32 v[34:35], v[98:99]
	v_mov_b64_e32 v[36:37], v[100:101]
	v_mov_b64_e32 v[38:39], v[102:103]
	v_mov_b64_e32 v[40:41], v[104:105]
	v_mov_b64_e32 v[42:43], v[106:107]
	v_mov_b64_e32 v[44:45], v[108:109]
	v_mov_b64_e32 v[46:47], v[110:111]
	v_mov_b64_e32 v[2:3], v[98:99]
	v_mov_b64_e32 v[4:5], v[100:101]
	v_mov_b64_e32 v[6:7], v[102:103]
	v_mov_b64_e32 v[8:9], v[104:105]
	v_mov_b64_e32 v[10:11], v[106:107]
	v_mov_b64_e32 v[12:13], v[108:109]
	v_mov_b64_e32 v[14:15], v[110:111]
	v_mov_b64_e32 v[124:125], v[108:109]
	v_mov_b64_e32 v[122:123], v[106:107]
	v_mov_b64_e32 v[120:121], v[104:105]
	v_mov_b64_e32 v[118:119], v[102:103]
	v_mov_b64_e32 v[116:117], v[100:101]
	v_mov_b64_e32 v[114:115], v[98:99]
	v_mov_b64_e32 v[112:113], v[96:97]
	v_mov_b64_e32 v[82:83], v[98:99]
	v_mov_b64_e32 v[84:85], v[100:101]
	v_mov_b64_e32 v[86:87], v[102:103]
	v_mov_b64_e32 v[88:89], v[104:105]
	v_mov_b64_e32 v[90:91], v[106:107]
	v_mov_b64_e32 v[92:93], v[108:109]
	v_mov_b64_e32 v[94:95], v[110:111]
	v_mov_b64_e32 v[50:51], v[98:99]
	v_mov_b64_e32 v[52:53], v[100:101]
	v_mov_b64_e32 v[54:55], v[102:103]
	v_mov_b64_e32 v[56:57], v[104:105]
	v_mov_b64_e32 v[58:59], v[106:107]
	v_mov_b64_e32 v[60:61], v[108:109]
	v_mov_b64_e32 v[62:63], v[110:111]
	v_mov_b64_e32 v[18:19], v[98:99]
	v_mov_b64_e32 v[20:21], v[100:101]
	v_mov_b64_e32 v[22:23], v[102:103]
	v_mov_b64_e32 v[24:25], v[104:105]
	v_mov_b64_e32 v[26:27], v[106:107]
	v_mov_b64_e32 v[28:29], v[108:109]
	v_mov_b64_e32 v[30:31], v[110:111]
	s_mov_b32 s60, 0
	v_mov_b32_e32 v201, v200
	v_mov_b32_e32 v199, v198
	v_mov_b32_e32 v217, 0xff800000
	v_mov_b32_e32 v197, 0xff800000
	v_add3_u32 v255, v220, v221, v222
	v_add3_u32 v195, v220, v221, v224
	v_add_u32_e32 v255, v255, v223
	v_add_u32_e32 v195, v195, v223
.LBB0_419:
	s_add_i32 s4, s60, 2
	s_lshl_b32 s6, s59, 14
	s_min_i32 s4, s4, s55
	s_add_i32 s5, s6, 0xffffc000
	s_cmp_gt_i32 s59, 0
	s_cselect_b32 s5, s5, 0x8000
	s_add_i32 s62, s53, s5
	s_lshl_b32 s63, s4, 17
	s_add_u32 s4, s8, s63
	s_addc_u32 s5, s9, 0
	s_mov_b32 m0, s62
	s_add_i32 s61, s6, 0
	global_load_lds_dwordx4 v192, s[4:5]
	s_add_i32 m0, s62, 0x2000
	s_cmp_gt_i32 s60, s54
	global_load_lds_dwordx4 v196, s[4:5]
	s_cbranch_scc1 .Lda_maskA
	v_add_u32_e32 v202, s61, v218
	v_add_u32_e32 v242, s52, v219
	ds_read_b128 v[128:131], v202
	ds_read_b128 v[132:135], v225
	ds_read_b128 v[144:147], v225 offset:512
	ds_read_b128 v[148:151], v202 offset:512
	v_add_u32_e32 v207, s61, v219
	s_waitcnt lgkmcnt(0)
	v_mfma_f32_32x32x16_bf16 v[160:175], v[128:131], v[132:135], 0
	ds_read_b128 v[128:131], v202 offset:8192
	ds_read_b128 v[152:155], v202 offset:8704
	ds_read_b128 v[156:159], v207
	ds_read_b128 v[176:179], v242
	ds_read_b128 v[180:183], v242 offset:512
	ds_read_b128 v[184:187], v207 offset:512
	s_waitcnt lgkmcnt(0)
	v_mfma_f32_32x32x16_bf16 v[160:175], v[156:159], v[176:179], v[160:175]
	ds_read_b128 v[156:159], v207 offset:8192
	ds_read_b128 v[188:191], v207 offset:8704
	v_mfma_f32_32x32x16_bf16 v[128:143], v[128:131], v[132:135], 0
	v_mfma_f32_32x32x16_bf16 v[160:175], v[148:151], v[144:147], v[160:175]
	s_waitcnt lgkmcnt(0)
	v_mfma_f32_32x32x16_bf16 v[128:143], v[156:159], v[176:179], v[128:143]
	v_mfma_f32_32x32x16_bf16 v[160:175], v[184:187], v[180:183], v[160:175]
	v_mfma_f32_32x32x16_bf16 v[128:143], v[152:155], v[144:147], v[128:143]
	s_nop 10
	v_max3_f32 v206, v160, v161, v162
	v_max3_f32 v206, v206, v163, v164
	v_max3_f32 v206, v206, v165, v166
	v_max3_f32 v206, v206, v167, v168
	v_mfma_f32_32x32x16_bf16 v[128:143], v[188:191], v[180:183], v[128:143]
	v_max3_f32 v206, v206, v169, v170
	v_max3_f32 v206, v206, v171, v172
	v_max3_f32 v206, v206, v173, v174
	v_max_f32_e32 v206, v206, v175
	s_nop 8
	v_max3_f32 v206, v206, v128, v129
	v_max3_f32 v206, v206, v130, v131
	v_max3_f32 v206, v206, v132, v133
	v_max3_f32 v206, v206, v134, v135
	v_max3_f32 v206, v206, v136, v137
	v_max3_f32 v206, v206, v138, v139
	v_max3_f32 v206, v206, v140, v141
	v_max3_f32 v206, v206, v142, v143
	v_cmp_lt_f32_e32 vcc, v217, v206
	s_mov_b64 s[6:7], -1
	ds_read_b128 v[144:147], v202 offset:1024
	ds_read_b128 v[148:151], v225 offset:1024
	ds_read_b128 v[208:211], v225 offset:1536
	ds_read_b128 v[226:229], v202 offset:1536
	s_cmp_eq_u64 vcc, 0
	s_cbranch_scc1 .Lda_nr0
	v_mov_b32_e32 v205, v206
	s_nop 1
	v_permlane32_swap_b32_e32 v206, v205
	v_max_f32_e32 v206, v206, v205
	v_max_f32_e32 v206, v199, v206
	v_sub_f32_e32 v205, v199, v206
	v_mov_b32_e32 v199, v206
	v_exp_f32_e32 v203, v205
	v_add_f32_e32 v217, 0x41000000, v206
	s_mov_b64 s[6:7], 0
	v_mul_f32_e32 v201, v201, v203
; DI unsigned pk2(float lo, float hi) { bf2_t v = __builtin_convertvector((f32x2){lo, hi}, bf2_t); return __builtin_bit_cast(unsigned, v); }
; #define WAIT_V(n) asm volatile("s_waitcnt vmcnt(" #n ")" ::: "memory")
; #define BAR __builtin_amdgcn_s_barrier()
; #define WAIT_V(n) asm volatile("s_waitcnt vmcnt(" #n ")" ::: "memory")
; #define BAR do { __builtin_amdgcn_sched_barrier(0); __builtin_amdgcn_s_barrier(); asm volatile("" ::: "memory"); __builtin_amdgcn_sched_barrier(0); } while (0)
; DI void dattn_unit2(const bf16_t* __restrict__ Qg, const bf16_t* __restrict__ Kg, const bf16_t* __restrict__ Vg, bf16_t* __restrict__ Og,
;                     int ntiles, int wave_tiles, float lam, const float* __restrict__ gsub, lds_t* shm) {
;     ...
;       if (resc[m]) { const float mnew = fmaxf(mrun[m], mx); alpha[m] = __builtin_amdgcn_exp2f(mrun[m] - mnew); mrun[m] = mnew; lrun[m] *= alpha[m]; }
;       const float msub = mrun[m] - msk;
;       float rs = 0.f;
; #pragma unroll
;       for (int kb = 0; kb < 2; ++kb)
; #pragma unroll
;         for (int s2 = 0; s2 < 2; ++s2) {
;           float e[8];
; #pragma unroll
;           for (int j = 0; j < 8; ++j) { e[j] = __builtin_amdgcn_exp2f(s[kb][8 * s2 + j] - msub); rs += e[j]; }
;           u32x4 w; w.x = pk2(e[0], e[1]); w.y = pk2(e[2], e[3]); w.z = pk2(e[4], e[5]); w.w = pk2(e[6], e[7]);
;           P[m][kb][s2] = __builtin_bit_cast(bf16x8, w);
;           __builtin_amdgcn_sched_barrier(0);
;         }
;       lrun[m] += rs;
;       __builtin_amdgcn_sched_barrier(0);
;     }
;     __builtin_amdgcn_sched_barrier(0);
;     WAIT_V(4); BAR;
;     issueV(kt + 2, slot2);
;     lds_t* V0 = shm + (so + va0); lds_t* V1 = shm + (so + va1);
; #pragma unroll
;     for (int m = 0; m < 2; ++m)
;       if (resc[m]) {
; #pragma unroll
;         for (int c = 0; c < NC; ++c) O[m][c] = O[m][c] * alpha[m];
;       }
; #pragma unroll
;     for (int ks = 0; ks < 4; ++ks) {
;       bf16x8 vf[NC];
; #pragma unroll
;       for (int c = 0; c < NC; ++c) { const int vo = 512 * c + 4096 * ks; vf[c] = tr_pair(V0 + vo, V1 + vo + 2048); }
.Lda_nr0:
	v_sub_f32_e32 v160, v160, v199
	v_sub_f32_e32 v161, v161, v199
	v_sub_f32_e32 v162, v162, v199
	v_exp_f32_e32 v160, v160
	v_sub_f32_e32 v163, v163, v199
	v_exp_f32_e32 v161, v161
	v_sub_f32_e32 v164, v164, v199
	v_exp_f32_e32 v162, v162
	v_sub_f32_e32 v165, v165, v199
	v_exp_f32_e32 v163, v163
	s_waitcnt lgkmcnt(0)
	v_mfma_f32_32x32x16_bf16 v[176:191], v[144:147], v[148:151], 0
	ds_read_b128 v[144:147], v202 offset:9216
	ds_read_b128 v[230:233], v202 offset:9728
	ds_read_b128 v[234:237], v207 offset:1024
	ds_read_b128 v[238:241], v242 offset:1024
	ds_read_b128 v[242:245], v242 offset:1536
	ds_read_b128 v[246:249], v207 offset:1536
	v_add_f32_e32 v201, v201, v160
	v_sub_f32_e32 v166, v166, v199
	v_exp_f32_e32 v164, v164
	v_add_f32_e32 v201, v201, v161
	v_sub_f32_e32 v167, v167, v199
	v_cvt_pk_bf16_f32 v160, v160, v161
	v_exp_f32_e32 v165, v165
	v_add_f32_e32 v201, v201, v162
	v_sub_f32_e32 v168, v168, v199
	v_exp_f32_e32 v166, v166
	v_add_f32_e32 v201, v201, v163
	v_sub_f32_e32 v169, v169, v199
	s_waitcnt lgkmcnt(0)
	v_mfma_f32_32x32x16_bf16 v[176:191], v[234:237], v[238:241], v[176:191]
	ds_read_b128 v[234:237], v207 offset:9216
	ds_read_b128 v[250:253], v207 offset:9728
	v_cvt_pk_bf16_f32 v161, v162, v163
	v_exp_f32_e32 v167, v167
	v_add_f32_e32 v201, v201, v164
	v_mfma_f32_32x32x16_bf16 v[144:159], v[144:147], v[148:151], 0
	v_sub_f32_e32 v170, v170, v199
	v_exp_f32_e32 v168, v168
	v_add_f32_e32 v201, v201, v165
	v_sub_f32_e32 v171, v171, v199
	v_cvt_pk_bf16_f32 v162, v164, v165
	v_mfma_f32_32x32x16_bf16 v[176:191], v[226:229], v[208:211], v[176:191]
	v_exp_f32_e32 v169, v169
	v_add_f32_e32 v201, v201, v166
	v_sub_f32_e32 v172, v172, v199
	v_exp_f32_e32 v170, v170
	v_add_f32_e32 v201, v201, v167
	s_waitcnt lgkmcnt(0)
	v_mfma_f32_32x32x16_bf16 v[144:159], v[234:237], v[238:241], v[144:159]
	v_sub_f32_e32 v173, v173, v199
	v_cvt_pk_bf16_f32 v163, v166, v167
	v_exp_f32_e32 v171, v171
	v_add_f32_e32 v201, v201, v168
	v_sub_f32_e32 v174, v174, v199
	v_mfma_f32_32x32x16_bf16 v[176:191], v[246:249], v[242:245], v[176:191]
	v_exp_f32_e32 v172, v172
	v_add_f32_e32 v201, v201, v169
	v_sub_f32_e32 v175, v175, v199
	v_cvt_pk_bf16_f32 v164, v168, v169
	v_exp_f32_e32 v173, v173
	v_mfma_f32_32x32x16_bf16 v[144:159], v[230:233], v[208:211], v[144:159]
	v_add_f32_e32 v201, v201, v170
	v_exp_f32_e32 v174, v174
	v_add_f32_e32 v201, v201, v171
	v_cvt_pk_bf16_f32 v165, v170, v171
	v_exp_f32_e32 v175, v175
	v_mfma_f32_32x32x16_bf16 v[144:159], v[250:253], v[242:245], v[144:159]
	v_max3_f32 v207, v176, v177, v178
	v_add_f32_e32 v201, v201, v172
	v_add_f32_e32 v201, v201, v173
	v_max3_f32 v207, v207, v179, v180
	v_cvt_pk_bf16_f32 v166, v172, v173
	v_add_f32_e32 v201, v201, v174
	v_max3_f32 v207, v207, v181, v182
	v_add_f32_e32 v201, v201, v175
	v_cvt_pk_bf16_f32 v167, v174, v175
	v_max3_f32 v207, v207, v183, v184
	v_max3_f32 v207, v207, v185, v186
	v_max3_f32 v207, v207, v187, v188
	v_max3_f32 v207, v207, v189, v190
	v_max_f32_e32 v207, v207, v191
	v_max3_f32 v207, v207, v144, v145
	v_max3_f32 v207, v207, v146, v147
	v_max3_f32 v207, v207, v148, v149
	v_max3_f32 v207, v207, v150, v151
	v_max3_f32 v207, v207, v152, v153
	v_max3_f32 v207, v207, v154, v155
	v_max3_f32 v207, v207, v156, v157
	v_max3_f32 v207, v207, v158, v159
	v_cmp_lt_f32_e64 s[4:5], v197, v207
	s_nop 0
	s_cmp_eq_u64 s[4:5], 0
	s_mov_b64 s[4:5], -1
	s_cbranch_scc1 .Lda_nr1
	v_mov_b32_e32 v205, v207
	s_nop 1
	v_permlane32_swap_b32_e32 v207, v205
	v_max_f32_e32 v207, v207, v205
	v_max_f32_e32 v207, v198, v207
	v_sub_f32_e32 v205, v198, v207
	v_mov_b32_e32 v198, v207
	v_exp_f32_e32 v202, v205
	v_add_f32_e32 v197, 0x41000000, v207
	s_mov_b64 s[4:5], 0
	v_mul_f32_e32 v200, v200, v202
.Lda_nr1:
.Lda_w1:
	s_waitcnt vmcnt(4)
	s_barrier
	s_setprio 1
	s_add_i32 m0, s62, 0xc000
	s_add_u32 s64, s28, s63
	s_addc_u32 s65, s29, 0
	global_load_lds_dwordx4 v192, s[64:65]
	s_add_i32 m0, s62, 0xe000
	s_cmp_gt_i32 s60, s54
	global_load_lds_dwordx4 v196, s[64:65]
	s_cbranch_scc1 .Lda_w2
	v_add_u32_e32 v204, s61, v255
	v_add_u32_e32 v205, s61, v195
	ds_read_b64_tr_b16 v[226:227], v204 offset:49152
	ds_read_b64_tr_b16 v[228:229], v205 offset:51200
	ds_read_b64_tr_b16 v[230:231], v204 offset:49664
	ds_read_b64_tr_b16 v[232:233], v205 offset:51712
	ds_read_b64_tr_b16 v[234:235], v204 offset:50176
	ds_read_b64_tr_b16 v[236:237], v205 offset:52224
	ds_read_b64_tr_b16 v[238:239], v204 offset:50688
	ds_read_b64_tr_b16 v[240:241], v205 offset:52736
	s_and_b64 vcc, exec, s[6:7]
	s_cbranch_vccnz .Lda_skip0
	v_pk_mul_f32 v[96:97], v[96:97], v[202:203] op_sel:[0,1]
	v_pk_mul_f32 v[98:99], v[98:99], v[202:203] op_sel:[0,1]
	v_pk_mul_f32 v[100:101], v[100:101], v[202:203] op_sel:[0,1]
	v_pk_mul_f32 v[102:103], v[102:103], v[202:203] op_sel:[0,1]
	v_pk_mul_f32 v[104:105], v[104:105], v[202:203] op_sel:[0,1]
	v_pk_mul_f32 v[106:107], v[106:107], v[202:203] op_sel:[0,1]
	v_pk_mul_f32 v[108:109], v[108:109], v[202:203] op_sel:[0,1]
	v_pk_mul_f32 v[110:111], v[110:111], v[202:203] op_sel:[0,1]
	v_pk_mul_f32 v[64:65], v[64:65], v[202:203] op_sel:[0,1]
	v_pk_mul_f32 v[66:67], v[66:67], v[202:203] op_sel:[0,1]
	v_pk_mul_f32 v[68:69], v[68:69], v[202:203] op_sel:[0,1]
	v_pk_mul_f32 v[70:71], v[70:71], v[202:203] op_sel:[0,1]
	v_pk_mul_f32 v[72:73], v[72:73], v[202:203] op_sel:[0,1]
	v_pk_mul_f32 v[74:75], v[74:75], v[202:203] op_sel:[0,1]
	v_pk_mul_f32 v[76:77], v[76:77], v[202:203] op_sel:[0,1]
	v_pk_mul_f32 v[78:79], v[78:79], v[202:203] op_sel:[0,1]
	v_pk_mul_f32 v[32:33], v[32:33], v[202:203] op_sel:[0,1]
	v_pk_mul_f32 v[34:35], v[34:35], v[202:203] op_sel:[0,1]
	v_pk_mul_f32 v[36:37], v[36:37], v[202:203] op_sel:[0,1]
	v_pk_mul_f32 v[38:39], v[38:39], v[202:203] op_sel:[0,1]
	v_pk_mul_f32 v[40:41], v[40:41], v[202:203] op_sel:[0,1]
	v_pk_mul_f32 v[42:43], v[42:43], v[202:203] op_sel:[0,1]
	v_pk_mul_f32 v[44:45], v[44:45], v[202:203] op_sel:[0,1]
	v_pk_mul_f32 v[46:47], v[46:47], v[202:203] op_sel:[0,1]
	v_pk_mul_f32 v[0:1], v[0:1], v[202:203] op_sel:[0,1]
	v_pk_mul_f32 v[2:3], v[2:3], v[202:203] op_sel:[0,1]
	v_pk_mul_f32 v[4:5], v[4:5], v[202:203] op_sel:[0,1]
	v_pk_mul_f32 v[6:7], v[6:7], v[202:203] op_sel:[0,1]
	v_pk_mul_f32 v[8:9], v[8:9], v[202:203] op_sel:[0,1]
	v_pk_mul_f32 v[10:11], v[10:11], v[202:203] op_sel:[0,1]
	v_pk_mul_f32 v[12:13], v[12:13], v[202:203] op_sel:[0,1]
	v_pk_mul_f32 v[14:15], v[14:15], v[202:203] op_sel:[0,1]
